# P1c/P1b prologue: the hoisted once-per-phase vmcnt(0) removed (source's counted vmcnt(6) governs the first tile too)
# speedup vs baseline: 1.0026x; 1.0026x over previous
; #define G_STAGE(bufoff, gbase, voff) do { _Pragma("unroll") for (int _i = 0; _i < 2; ++_i) \
;         __builtin_amdgcn_global_load_lds((const unsigned*)((const char*)(gbase) + (voff)[_i]), (LAS unsigned*)(lds + (bufoff) + ldsw + _i * 8192), 16, 0, 0); } while (0)
; #define G_WAIT_V(n) asm volatile("s_waitcnt vmcnt(" #n ")" ::: "memory")
; #define G_BAR __builtin_amdgcn_s_barrier()
; template <int MODE  , class Epi, class Sched>
; __device__ __forceinline__ void gemm_phase(LAS unsigned char* lds, const GemmDesc g, const Sched& S, const Epi& E) {
;     ...
;     for (int i = 0; i < 2; ++i) { int R, C; stage_rc(tid * 16 + i * 8192, R, C); const int Rb = (R & ~31) + perm32(R & 31);
;         voffA[i] = (unsigned)(R * g.lda + C) * 2u; voffB[i] = (unsigned)(Rb * g.ldb + C) * 2u; }
;     const size_t kstep = (size_t)(BK * 2);
;     const size_t hstepA = (size_t)HALF * g.lda * 2, hstepB = (size_t)HALF * g.ldb * 2;
;     const size_t khb = (size_t)nt * kstep;
;     const unsigned ldsw = (unsigned)wid * 1024u;
;     const int aoff = lds_byte(wr * 64 + fr, fq * 8), boff = lds_byte(wc * 32 + fr, fq * 8);
;     ...
;     G_STAGE(G_SB(0, 0), cB, voffB); G_STAGE(G_SA(0, 0), cA, voffA); G_STAGE(G_SB(0, 1), cB + hstepB, voffB); G_STAGE(G_SA(0, 1), cA + hstepA, voffA);
;     if (wr == 1) G_BAR;
;     G_WAIT_V(4); G_BAR;
;     G_STAGE(G_SB(1, 0), cB + kstep, voffB); G_STAGE(G_SA(1, 0), cA + kstep, voffA); G_STAGE(G_SB(1, 1), cB + hstepB + kstep, voffB);
;     G_WAIT_V(6); G_BAR;
.LBB0_518:
	s_add_u32 s4, s26, 0x39615000
	s_addc_u32 s5, s27, 0
	s_lshl_b32 s2, s2, 5
	s_mov_b64 s[16:17], 0x80
	s_and_b32 s11, s2, 0x60
	s_add_i32 m0, s55, 0x18000
	v_lshl_add_u64 v[8:9], v[8:9], 0, s[16:17]
	s_lshl_b32 s10, s0, 13
	s_lshl_b32 s18, s11, 7
	s_waitcnt vmcnt(4)
	s_barrier
	global_load_lds_dwordx4 v[8:9], off
	v_lshl_add_u64 v[6:7], v[6:7], 0, s[16:17]
	s_add_i32 m0, s55, 0x1a000
	s_add_i32 s60, s55, 0x8000
	s_add_i32 s61, s55, 0xa000
	global_load_lds_dwordx4 v[6:7], off
	v_lshl_add_u64 v[4:5], v[4:5], 0, s[16:17]
	s_mov_b32 m0, s60
	s_add_u32 s2, s40, 0x44080
	global_load_lds_dwordx4 v[4:5], off
	v_lshl_add_u64 v[2:3], v[2:3], 0, s[16:17]
	s_mov_b32 m0, s61
	s_addc_u32 s3, s41, 0
	global_load_lds_dwordx4 v[2:3], off
	s_add_i32 m0, s55, 0x1c000
	v_lshl_add_u64 v[2:3], s[2:3], 0, v[148:149]
	global_load_lds_dwordx4 v[2:3], off
	v_lshl_add_u64 v[2:3], s[2:3], 0, v[152:153]
	s_add_i32 m0, s55, 0x1e000
	s_mov_b64 s[2:3], 0x44080
	global_load_lds_dwordx4 v[2:3], off
	v_lshrrev_b32_e32 v3, 1, v10
	v_and_b32_e32 v3, 24, v3
	v_and_b32_e32 v2, 15, v10
	v_lshlrev_b32_e32 v4, 1, v3
	v_lshl_or_b32 v1, s0, 6, v2
	v_lshl_or_b32 v2, v2, 6, v4
	v_lshlrev_b32_e32 v4, 2, v10
	v_or_b32_e32 v192, s11, v3
	v_and_b32_e32 v4, 32, v4
	v_lshlrev_b32_e32 v154, 2, v192
	v_bitop3_b32 v5, v2, s10, v4 bitop3:0xde
	v_bitop3_b32 v191, v2, s18, v4 bitop3:0xde
	v_lshl_add_u64 v[2:3], s[26:27], 0, v[154:155]
	s_mov_b64 s[10:11], 0x3960f000
	v_lshl_add_u64 v[156:157], v[2:3], 0, s[10:11]
	v_lshrrev_b32_e32 v3, 1, v11
	v_mul_lo_u32 v2, v13, s1
	s_movk_i32 s0, 0x4400
	v_mad_u64_u32 v[2:3], s[10:11], v3, s0, v[2:3]
	v_or_b32_e32 v2, v2, v12
	v_add_lshl_u32 v154, v2, v14, 1
	v_lshrrev_b32_e32 v3, 1, v15
	v_mul_lo_u32 v2, v16, s1
	v_mad_u64_u32 v[2:3], s[0:1], v3, s0, v[2:3]
	s_waitcnt vmcnt(6)
	v_or_b32_e32 v2, v2, v17
	s_add_i32 s66, 0, 0x10000
	s_add_i32 s68, 0, 0x14000
	v_lshl_add_u64 v[158:159], v[154:155], 0, s[2:3]
	v_add_lshl_u32 v154, v2, v18, 1
	v_add_u32_e32 v193, s66, v191
	v_add_u32_e32 v195, s68, v191
	s_add_i32 s66, s66, s54
	s_add_i32 s68, s68, s54
	v_lshl_add_u64 v[160:161], v[154:155], 0, s[2:3]
	s_movk_i32 s62, 0x199
	v_add_u32_e32 v194, 0, v5
	s_mov_b32 s63, 0xc2200000
	s_add_i32 s64, s55, 0xc000
	s_add_i32 s65, s55, 0xe000
	s_add_i32 s67, s66, 0x2000
	s_add_i32 s69, s68, 0x2000
	v_mov_b32_e32 v196, 0x42200000
	s_barrier
	ds_read_b128 v[232:235], v193
	ds_read_b128 v[236:239], v193 offset:1024
	ds_read_b128 v[240:243], v193 offset:2048
	ds_read_b128 v[244:247], v193 offset:3072
	s_branch .LBB0_520
